# latent scan item prologue: eight parameter loads batched with counted vmcnt before the LDS writes, on v36
# baseline (speedup 1.0000x reference)
.LBB0_436:
	s_andn2_b64 vcc, exec, s[8:9]
	s_cbranch_vccnz .LBB0_464
	s_waitcnt vmcnt(0)
	v_mov_b32_e32 v52, v254
	s_bfe_u32 s36, s95, 0x30001
	s_mov_b32 s37, s27
	v_cmp_lt_i32_e32 vcc, 63, v52
	s_barrier
	s_and_saveexec_b64 s[8:9], vcc
	s_xor_b64 s[8:9], exec, s[8:9]
	s_lshl_b32 s2, s36, 6
	s_or_saveexec_b64 s[12:13], s[8:9]
	s_and_b32 s33, s95, 1
	s_or_b32 s26, s33, s88
	v_mov_b32_e32 v148, s2
	v_ashrrev_i32_e32 v53, 31, v52
	s_xor_b64 exec, exec, s[12:13]
	s_cbranch_execz .LBB0_441
	s_load_dwordx2 s[14:15], s[84:85], 0x80
	s_load_dwordx4 s[8:11], s[84:85], 0xa8
	s_load_dwordx2 s[16:17], s[84:85], 0xb8
	s_mul_i32 s20, s26, 0x1a00
	s_mul_hi_u32 s2, s26, 0x1a00
	s_waitcnt lgkmcnt(0)
	s_add_u32 s14, s14, s20
	s_addc_u32 s15, s15, s2
	s_lshl_b32 s2, s36, 6
	v_add_u32_e32 v0, s2, v52
	v_ashrrev_i32_e32 v1, 31, v0
	v_lshl_add_u64 v[2:3], v[0:1], 2, s[14:15]
	global_load_dword v6, v[2:3], off
	v_mov_b32_e32 v4, 0x10400
	global_load_dword v7, v[2:3], off offset:2048
	v_lshl_add_u32 v4, v52, 2, v4
	v_add_u32_e32 v0, 0x400, v0
	v_mov_b32_e32 v148, s2
	v_ashrrev_i32_e32 v1, 31, v0
	v_lshl_add_u64 v[0:1], v[0:1], 2, s[14:15]
	global_load_dword v8, v[0:1], off
	v_lshl_add_u64 v[0:1], v[52:53], 2, s[14:15]
	s_movk_i32 s14, 0x1000
	v_add_co_u32_e32 v0, vcc, s14, v0
	v_readlane_b32 s14, v255, 33
	s_nop 0
	v_addc_co_u32_e32 v1, vcc, 0, v1, vcc
	global_load_dword v9, v[0:1], off offset:2048
	global_load_dword v10, v[0:1], off offset:2304
	s_or_b32 s14, s2, s14
	v_add_u32_e32 v0, s14, v52
	v_ashrrev_i32_e32 v1, 31, v0
	v_lshlrev_b64 v[0:1], 2, v[0:1]
	v_readlane_b32 s15, v255, 34
	v_lshl_add_u64 v[2:3], s[8:9], 0, v[0:1]
	global_load_dword v11, v[2:3], off
	v_lshl_add_u64 v[2:3], s[10:11], 0, v[0:1]
	v_lshl_add_u64 v[0:1], s[16:17], 0, v[0:1]
	global_load_dword v12, v[2:3], off
	s_nop 0
	global_load_dword v13, v[0:1], off
	s_waitcnt vmcnt(6)
	ds_write2st64_b32 v4, v6, v7 offset1:1
	s_waitcnt vmcnt(4)
	ds_write2st64_b32 v4, v8, v9 offset0:2 offset1:3
	s_waitcnt vmcnt(2)
	ds_write2st64_b32 v4, v10, v11 offset0:4 offset1:5
	s_waitcnt vmcnt(0)
	ds_write2st64_b32 v4, v12, v13 offset0:6 offset1:7
